# speedup vs baseline: 1.0471x; 1.0034x over previous
; #define STAGE_A(Pp, br, kt) do { const size_t _uo = ((size_t)(br) * g.K + (kt) * BK) * 2; \
;     __builtin_amdgcn_global_load_lds((const unsigned*)(pb + _uo), (unsigned*)((char*)(Pp) + tb0), 16, 0, 0); \
;     __builtin_amdgcn_global_load_lds((const unsigned*)(pb + _uo + (size_t)g.K * 128), (unsigned*)((char*)(Pp) + tb0 + 8192), 16, 0, 0); } while (0)
; #define WAIT_V(n) asm volatile("s_waitcnt vmcnt(" #n ")" ::: "memory")
; #define BAR __builtin_amdgcn_s_barrier()
; __device__ __forceinline__ void gemm_phase(const int WV, const GemmArgs& g, int tile0) {
;     ...
;   for (int vt = tile0 + blockIdx.x; vt < g.nTiles; vt += gridDim.x) {
;     int wgid = vt;
;     { int q = nwg / NXCD, r = nwg % NXCD, xcd = wgid % NXCD, off = wgid / NXCD;
;       wgid = (xcd < r ? xcd * (q + 1) : r * (q + 1) + (xcd - r) * q) + off; }
;     int nig = WGM * nN, gid = wgid / nig, fm = gid * WGM, gsz = min(nM - fm, WGM);
;     int pm = fm + ((wgid % nig) % gsz), pn = (wgid % nig) / gsz, brow = pm * BM, bcol = pn * BM;
;     f32x4 acc[2][2][4][2] = {};
;     bf16x8 At[4][2], B0[2][2], B1[2][2];
;     __syncthreads();
;     STAGE_B(SB(0, 0), bcol, 0); STAGE_A(SA(0, 0), brow, 0);
;     STAGE_B(SB(0, 1), bcol + HALF, 0); STAGE_A(SA(0, 1), brow + HALF, 0);
;     if (wr == 1) BAR;
;     WAIT_V(4); BAR;
;     STAGE_B(SB(1, 0), bcol, 1); STAGE_A(SA(1, 0), brow, 1); STAGE_B(SB(1, 1), bcol + HALF, 1);
;     WAIT_V(6); BAR;
.LBB0_432:
	s_or_b64 exec, exec, s[12:13]
	v_add_u32_e32 v146, 0x18000, v174
	v_add_u32_e32 v147, 0x1a000, v174
	v_readfirstlane_b32 s6, v146
	v_lshl_add_u64 v[2:3], v[2:3], 0, s[82:83]
	s_mov_b32 m0, s6
	v_readfirstlane_b32 s6, v147
	v_add_u32_e32 v148, 0x8000, v174
	s_waitcnt vmcnt(4)
	s_barrier
	global_load_lds_dwordx4 v[2:3], off
	v_lshl_add_u64 v[2:3], v[4:5], 0, s[82:83]
	s_mov_b32 m0, s6
	v_readfirstlane_b32 s6, v148
	v_add_u32_e32 v149, 0xa000, v174
	global_load_lds_dwordx4 v[2:3], off
	v_lshl_add_u64 v[2:3], v[8:9], 0, s[82:83]
	s_mov_b32 m0, s6
	v_readfirstlane_b32 s6, v149
	v_add_u32_e32 v150, 0x1c000, v174
	global_load_lds_dwordx4 v[2:3], off
	v_lshl_add_u64 v[2:3], v[6:7], 0, s[82:83]
	s_mov_b32 m0, s6
	v_readfirstlane_b32 s6, v150
	v_add_u32_e32 v151, 0x1e000, v174
	global_load_lds_dwordx4 v[2:3], off
	v_lshl_add_u64 v[2:3], v[10:11], 0, s[82:83]
	s_mov_b32 m0, s6
	v_readfirstlane_b32 s6, v151
	global_load_lds_dwordx4 v[2:3], off
	v_lshl_add_u64 v[2:3], v[12:13], 0, s[82:83]
	s_mov_b32 m0, s6
	s_ashr_i32 s51, s50, 31
	global_load_lds_dwordx4 v[2:3], off
	s_add_u32 s6, s50, 0x80
	s_addc_u32 s7, s51, 0
	s_mul_i32 s7, s57, s7
	s_mul_hi_u32 s12, s57, s6
	s_add_i32 s7, s12, s7
	s_mul_i32 s6, s57, s6
	s_add_u32 s12, s88, s6
	s_addc_u32 s13, s89, s7
	s_lshl_b64 s[6:7], s[50:51], 1
	s_add_u32 s20, s6, 0x180
	s_addc_u32 s21, s7, 0
	s_mul_i32 s21, s24, s21
	s_mul_hi_u32 s34, s24, s20
	s_add_i32 s34, s34, s21
	s_mul_i32 s20, s24, s20
	s_add_u32 s20, s88, s20
	s_mul_i32 s27, s57, s50
	s_addc_u32 s21, s89, s34
	s_mul_hi_i32 s26, s57, s50
	s_add_u32 vcc_lo, s88, s27
	s_addc_u32 vcc_hi, s89, s26
	s_add_u32 s6, s6, 0x80
	s_addc_u32 s7, s7, 0
	s_mul_i32 s7, s24, s7
	s_mul_hi_u32 s26, s24, s6
	s_waitcnt vmcnt(6)
	s_add_i32 s7, s26, s7
	s_mul_i32 s6, s24, s6
	s_add_u32 s26, s88, s6
	v_mov_b32_e32 v2, 0
	s_addc_u32 s27, s89, s7
	s_mov_b32 s56, 0
	s_movk_i32 s6, 0x80
	v_mov_b32_e32 v3, v2
	v_mov_b32_e32 v4, v2
	v_mov_b32_e32 v5, v2
	v_mov_b32_e32 v6, v2
	v_mov_b32_e32 v7, v2
	v_mov_b32_e32 v8, v2
	v_mov_b32_e32 v9, v2
	v_mov_b32_e32 v10, v2
	v_mov_b32_e32 v11, v2
	v_mov_b32_e32 v12, v2
	v_mov_b32_e32 v13, v2
	v_mov_b32_e32 v14, v2
	v_mov_b32_e32 v15, v2
	v_mov_b32_e32 v16, v2
	v_mov_b32_e32 v17, v2
	v_mov_b32_e32 v18, v2
	v_mov_b32_e32 v19, v2
	v_mov_b32_e32 v20, v2
	v_mov_b32_e32 v21, v2
	v_mov_b32_e32 v22, v2
	v_mov_b32_e32 v23, v2
	v_mov_b32_e32 v24, v2
	v_mov_b32_e32 v25, v2
	v_mov_b32_e32 v26, v2
	v_mov_b32_e32 v27, v2
	v_mov_b32_e32 v28, v2
	v_mov_b32_e32 v29, v2
	v_mov_b32_e32 v30, v2
	v_mov_b32_e32 v31, v2
	v_mov_b32_e32 v32, v2
	v_mov_b32_e32 v33, v2
	v_mov_b32_e32 v34, v2
	v_mov_b32_e32 v35, v2
	v_mov_b32_e32 v36, v2
	v_mov_b32_e32 v37, v2
	v_mov_b32_e32 v38, v2
	v_mov_b32_e32 v39, v2
	v_mov_b32_e32 v40, v2
	v_mov_b32_e32 v41, v2
	v_mov_b32_e32 v42, v2
	v_mov_b32_e32 v43, v2
	v_mov_b32_e32 v44, v2
	v_mov_b32_e32 v45, v2
	v_mov_b32_e32 v46, v2
	v_mov_b32_e32 v47, v2
	v_mov_b32_e32 v48, v2
	v_mov_b32_e32 v49, v2
	v_mov_b32_e32 v50, v2
	v_mov_b32_e32 v51, v2
	v_mov_b32_e32 v52, v2
	v_mov_b32_e32 v53, v2
	v_mov_b32_e32 v54, v2
	v_mov_b32_e32 v55, v2
	v_mov_b32_e32 v56, v2
	v_mov_b32_e32 v57, v2
	v_mov_b32_e32 v58, v2
	v_mov_b32_e32 v59, v2
	v_mov_b32_e32 v60, v2
	v_mov_b32_e32 v61, v2
	v_mov_b32_e32 v62, v2
	v_mov_b32_e32 v63, v2
	v_mov_b32_e32 v64, v2
	v_mov_b32_e32 v65, v2
	v_mov_b32_e32 v66, v2
	v_mov_b32_e32 v67, v2
	v_mov_b32_e32 v68, v2
	v_mov_b32_e32 v69, v2
	v_mov_b32_e32 v70, v2
	v_mov_b32_e32 v71, v2
	v_mov_b32_e32 v72, v2
	v_mov_b32_e32 v73, v2
	v_mov_b32_e32 v74, v2
	v_mov_b32_e32 v75, v2
	v_mov_b32_e32 v76, v2
	v_mov_b32_e32 v77, v2
	v_mov_b32_e32 v78, v2
	v_mov_b32_e32 v79, v2
	v_mov_b32_e32 v80, v2
	v_mov_b32_e32 v81, v2
	v_mov_b32_e32 v82, v2
	v_mov_b32_e32 v83, v2
	v_mov_b32_e32 v84, v2
	v_mov_b32_e32 v85, v2
	v_mov_b32_e32 v86, v2
	v_mov_b32_e32 v87, v2
	v_mov_b32_e32 v88, v2
	v_mov_b32_e32 v89, v2
	v_mov_b32_e32 v90, v2
	v_mov_b32_e32 v91, v2
	v_mov_b32_e32 v92, v2
	v_mov_b32_e32 v93, v2
	v_mov_b32_e32 v94, v2
	v_mov_b32_e32 v95, v2
	s_nop 0
	v_mov_b32_e32 v96, v2
	v_mov_b32_e32 v97, v2
	v_mov_b32_e32 v98, v2
	v_mov_b32_e32 v99, v2
	v_mov_b32_e32 v100, v2
	v_mov_b32_e32 v101, v2
	v_mov_b32_e32 v102, v2
	v_mov_b32_e32 v103, v2
	v_mov_b32_e32 v104, v2
	v_mov_b32_e32 v105, v2
	v_mov_b32_e32 v106, v2
	v_mov_b32_e32 v107, v2
	v_mov_b32_e32 v108, v2
	v_mov_b32_e32 v109, v2
	v_mov_b32_e32 v110, v2
	v_mov_b32_e32 v111, v2
	v_mov_b32_e32 v112, v2
	v_mov_b32_e32 v113, v2
	v_mov_b32_e32 v114, v2
	v_mov_b32_e32 v115, v2
	v_mov_b32_e32 v116, v2
	v_mov_b32_e32 v117, v2
	v_mov_b32_e32 v118, v2
	v_mov_b32_e32 v119, v2
	v_mov_b32_e32 v120, v2
	v_mov_b32_e32 v121, v2
	v_mov_b32_e32 v122, v2
	v_mov_b32_e32 v123, v2
	v_mov_b32_e32 v124, v2
	v_mov_b32_e32 v125, v2
	v_mov_b32_e32 v126, v2
	v_mov_b32_e32 v127, v2
	v_mov_b32_e32 v128, v2
	v_mov_b32_e32 v129, v2
	s_barrier
	v_readfirstlane_b32 s34, v162
	s_nop 3
	s_cmp_ge_u32 s34, 0x100
	s_cbranch_scc0 .Lgprio_skip
	s_setprio 1
; #define STAGE_A(Pp, br, kt) do { const size_t _uo = ((size_t)(br) * g.K + (kt) * BK) * 2; \
;     __builtin_amdgcn_global_load_lds((const unsigned*)(pb + _uo), (unsigned*)((char*)(Pp) + tb0), 16, 0, 0); \
;     __builtin_amdgcn_global_load_lds((const unsigned*)(pb + _uo + (size_t)g.K * 128), (unsigned*)((char*)(Pp) + tb0 + 8192), 16, 0, 0); } while (0)
; #define LDA(dst, b, h) _Pragma("unroll") for (int m = 0; m < 4; ++m) _Pragma("unroll") for (int k = 0; k < 2; ++k) \
;     dst[m][k] = *reinterpret_cast<const bf16x8*>((char*)SA(b, h) + lds_byte(wr * 64 + m * 16 + fr, k * 32 + fq * 8))
; #define LDB(dst, b, h) _Pragma("unroll") for (int n = 0; n < 2; ++n) _Pragma("unroll") for (int k = 0; k < 2; ++k) \
;     dst[n][k] = *reinterpret_cast<const bf16x8*>((char*)SB(b, h) + lds_byte(wc * 32 + n * 16 + fr, k * 32 + fq * 8))
; #define MMA(ai, bj, At, Bq) do { __builtin_amdgcn_s_setprio(1); \
;     _Pragma("unroll") for (int m = 0; m < 4; ++m) _Pragma("unroll") for (int n = 0; n < 2; ++n) _Pragma("unroll") for (int k = 0; k < 2; ++k) \
;       acc[ai][bj][m][n] = __builtin_amdgcn_mfma_f32_16x16x32_bf16(At[m][k], Bq[n][k], acc[ai][bj][m][n], 0, 0, 0); \
;     __builtin_amdgcn_s_setprio(0); } while (0)
; #define WAIT_V(n) asm volatile("s_waitcnt vmcnt(" #n ")" ::: "memory")
; #define WAIT_L(n) asm volatile("s_waitcnt lgkmcnt(" #n ")" ::: "memory")
; #define BAR __builtin_amdgcn_s_barrier()
; #define SCHED __builtin_amdgcn_sched_barrier(0)
; __device__ __forceinline__ void gemm_phase(const int WV, const GemmArgs& g, int tile0) {
;     ...
;     for (int t = 0; t < nt - 2; t += 2) {
;       LDB(B0, 0, 0); SCHED; LDA(At, 0, 0); STAGE_A(SA(1, 1), brow + HALF, t + 1);
;       WAIT_L(8); BAR; WAIT_L(0); MMA(0, 0, At, B0); BAR; SCHED;
;       LDB(B1, 0, 1); STAGE_B(SB(0, 0), bcol, t + 2);
;       BAR; WAIT_L(0); MMA(0, 1, At, B1); BAR;
;       LDA(At, 0, 1); STAGE_A(SA(0, 0), brow, t + 2);
;       BAR; WAIT_L(0); MMA(1, 0, At, B0); BAR; SCHED;
;       STAGE_B(SB(0, 1), bcol + HALF, t + 2);
;       WAIT_V(6); BAR; MMA(1, 1, At, B1); BAR;
.Lgprio_skip:
.LBB0_433:
	s_nop 0
	ds_read_b128 v[154:157], v175
	ds_read_b128 v[158:161], v175 offset:1024
	ds_read_b128 v[184:187], v175 offset:2048
	ds_read_b128 v[188:191], v175 offset:3072
	v_add_u32_e32 v152, 0xc000, v174
	v_lshl_add_u64 v[240:241], s[12:13], 0, v[138:139]
	v_readfirstlane_b32 s7, v152
	v_add_u32_e32 v153, 0xe000, v174
	v_lshl_add_u64 v[224:225], v[240:241], 0, s[82:83]
	s_mov_b32 m0, s7
	v_lshl_add_u64 v[242:243], s[20:21], 0, v[138:139]
	v_readfirstlane_b32 s7, v153
	ds_read_b128 v[192:195], v176
	ds_read_b128 v[196:199], v176 offset:1024
	ds_read_b128 v[200:203], v177
	ds_read_b128 v[204:207], v177 offset:1024
	ds_read_b128 v[208:211], v178
	ds_read_b128 v[212:215], v178 offset:1024
	ds_read_b128 v[216:219], v179
	ds_read_b128 v[220:223], v179 offset:1024
	global_load_lds_dwordx4 v[224:225], off
	v_lshl_add_u64 v[224:225], v[242:243], 0, s[82:83]
	s_mov_b32 m0, s7
	s_nop 0
	global_load_lds_dwordx4 v[224:225], off
	s_waitcnt lgkmcnt(8)
	s_barrier
	s_waitcnt lgkmcnt(0)
	s_waitcnt lgkmcnt(0)
	v_mfma_f32_16x16x32_bf16 v[126:129], v[192:195], v[154:157], v[126:129]
	v_mfma_f32_16x16x32_bf16 v[122:125], v[192:195], v[184:187], v[122:125]
	v_mfma_f32_16x16x32_bf16 v[118:121], v[200:203], v[154:157], v[118:121]
	v_mfma_f32_16x16x32_bf16 v[114:117], v[200:203], v[184:187], v[114:117]
	v_mfma_f32_16x16x32_bf16 v[110:113], v[208:211], v[154:157], v[110:113]
	v_mfma_f32_16x16x32_bf16 v[106:109], v[208:211], v[184:187], v[106:109]
	v_mfma_f32_16x16x32_bf16 v[102:105], v[216:219], v[154:157], v[102:105]
	v_mfma_f32_16x16x32_bf16 v[98:101], v[216:219], v[184:187], v[98:101]
	v_mfma_f32_16x16x32_bf16 v[126:129], v[196:199], v[158:161], v[126:129]
	v_mfma_f32_16x16x32_bf16 v[122:125], v[196:199], v[188:191], v[122:125]
	v_mfma_f32_16x16x32_bf16 v[118:121], v[204:207], v[158:161], v[118:121]
	v_mfma_f32_16x16x32_bf16 v[114:117], v[204:207], v[188:191], v[114:117]
	v_mfma_f32_16x16x32_bf16 v[110:113], v[212:215], v[158:161], v[110:113]
	v_mfma_f32_16x16x32_bf16 v[106:109], v[212:215], v[188:191], v[106:109]
	v_mfma_f32_16x16x32_bf16 v[102:105], v[220:223], v[158:161], v[102:105]
	v_mfma_f32_16x16x32_bf16 v[98:101], v[220:223], v[188:191], v[98:101]
	s_barrier
	s_add_i32 s56, s56, 2
	s_cmp_ge_u32 s6, s22
	s_cselect_b32 s7, s23, 0
	s_add_i32 s7, s7, s6
	s_add_u32 s34, s8, s7
	s_addc_u32 s35, s9, 0
	v_lshl_add_u64 v[244:245], s[34:35], 1, v[134:135]
	v_readfirstlane_b32 s34, v0
	s_mov_b32 m0, s34
	v_readfirstlane_b32 s34, v140
	s_nop 0
	ds_read_b128 v[224:227], v180
	ds_read_b128 v[228:231], v180 offset:1024
	ds_read_b128 v[232:235], v180 offset:2048
	ds_read_b128 v[236:239], v180 offset:3072
	global_load_lds_dwordx4 v[244:245], off
	v_lshl_add_u64 v[244:245], v[244:245], 0, s[42:43]
	s_mov_b32 m0, s34
	s_nop 0
	global_load_lds_dwordx4 v[244:245], off
	s_barrier
	s_waitcnt lgkmcnt(0)
	s_waitcnt lgkmcnt(0)
	v_mfma_f32_16x16x32_bf16 v[94:97], v[192:195], v[224:227], v[94:97]
	v_mfma_f32_16x16x32_bf16 v[90:93], v[192:195], v[232:235], v[90:93]
	v_mfma_f32_16x16x32_bf16 v[86:89], v[200:203], v[224:227], v[86:89]
	v_mfma_f32_16x16x32_bf16 v[82:85], v[200:203], v[232:235], v[82:85]
	v_mfma_f32_16x16x32_bf16 v[78:81], v[208:211], v[224:227], v[78:81]
	v_mfma_f32_16x16x32_bf16 v[74:77], v[208:211], v[232:235], v[74:77]
	v_mfma_f32_16x16x32_bf16 v[70:73], v[216:219], v[224:227], v[70:73]
	v_mfma_f32_16x16x32_bf16 v[66:69], v[216:219], v[232:235], v[66:69]
	v_mfma_f32_16x16x32_bf16 v[94:97], v[196:199], v[228:231], v[94:97]
	v_mfma_f32_16x16x32_bf16 v[90:93], v[196:199], v[236:239], v[90:93]
	v_mfma_f32_16x16x32_bf16 v[86:89], v[204:207], v[228:231], v[86:89]
	v_mfma_f32_16x16x32_bf16 v[82:85], v[204:207], v[236:239], v[82:85]
	v_mfma_f32_16x16x32_bf16 v[78:81], v[212:215], v[228:231], v[78:81]
	v_mfma_f32_16x16x32_bf16 v[74:77], v[212:215], v[236:239], v[74:77]
	v_mfma_f32_16x16x32_bf16 v[70:73], v[220:223], v[228:231], v[70:73]
	v_mfma_f32_16x16x32_bf16 v[66:69], v[220:223], v[236:239], v[66:69]
	v_lshl_add_u64 v[244:245], vcc, 0, v[138:139]
	v_readfirstlane_b32 s34, v174
	v_lshl_add_u64 v[246:247], v[244:245], 0, s[38:39]
	s_mov_b32 m0, s34
	s_barrier
	s_nop 0
	ds_read_b128 v[192:195], v176 offset:16384
	ds_read_b128 v[196:199], v176 offset:17408
	ds_read_b128 v[200:203], v177 offset:16384
	ds_read_b128 v[204:207], v177 offset:17408
	ds_read_b128 v[208:211], v178 offset:16384
	ds_read_b128 v[212:215], v178 offset:17408
	ds_read_b128 v[216:219], v179 offset:16384
	ds_read_b128 v[220:223], v179 offset:17408
	global_load_lds_dwordx4 v[246:247], off
	v_lshl_add_u64 v[246:247], s[26:27], 0, v[138:139]
	v_readfirstlane_b32 s34, v141
	v_lshl_add_u64 v[248:249], v[246:247], 0, s[38:39]
	s_mov_b32 m0, s34
	s_nop 0
	global_load_lds_dwordx4 v[248:249], off
	s_barrier
	s_waitcnt lgkmcnt(0)
	s_waitcnt lgkmcnt(0)
	v_mfma_f32_16x16x32_bf16 v[62:65], v[192:195], v[154:157], v[62:65]
	v_mfma_f32_16x16x32_bf16 v[58:61], v[192:195], v[184:187], v[58:61]
	v_mfma_f32_16x16x32_bf16 v[54:57], v[200:203], v[154:157], v[54:57]
	v_mfma_f32_16x16x32_bf16 v[50:53], v[200:203], v[184:187], v[50:53]
	v_mfma_f32_16x16x32_bf16 v[46:49], v[208:211], v[154:157], v[46:49]
	v_mfma_f32_16x16x32_bf16 v[42:45], v[208:211], v[184:187], v[42:45]
	v_mfma_f32_16x16x32_bf16 v[38:41], v[216:219], v[154:157], v[38:41]
	v_mfma_f32_16x16x32_bf16 v[34:37], v[216:219], v[184:187], v[34:37]
	v_mfma_f32_16x16x32_bf16 v[62:65], v[196:199], v[158:161], v[62:65]
	v_mfma_f32_16x16x32_bf16 v[58:61], v[196:199], v[188:191], v[58:61]
	v_mfma_f32_16x16x32_bf16 v[54:57], v[204:207], v[158:161], v[54:57]
	v_mfma_f32_16x16x32_bf16 v[50:53], v[204:207], v[188:191], v[50:53]
	v_mfma_f32_16x16x32_bf16 v[46:49], v[212:215], v[158:161], v[46:49]
	v_mfma_f32_16x16x32_bf16 v[42:45], v[212:215], v[188:191], v[42:45]
	v_mfma_f32_16x16x32_bf16 v[38:41], v[220:223], v[158:161], v[38:41]
	v_mfma_f32_16x16x32_bf16 v[34:37], v[220:223], v[188:191], v[34:37]
	s_barrier
; #define STAGE_A(Pp, br, kt) do { const size_t _uo = ((size_t)(br) * g.K + (kt) * BK) * 2; \
;     __builtin_amdgcn_global_load_lds((const unsigned*)(pb + _uo), (unsigned*)((char*)(Pp) + tb0), 16, 0, 0); \
;     __builtin_amdgcn_global_load_lds((const unsigned*)(pb + _uo + (size_t)g.K * 128), (unsigned*)((char*)(Pp) + tb0 + 8192), 16, 0, 0); } while (0)
; #define LDA(dst, b, h) _Pragma("unroll") for (int m = 0; m < 4; ++m) _Pragma("unroll") for (int k = 0; k < 2; ++k) \
;     dst[m][k] = *reinterpret_cast<const bf16x8*>((char*)SA(b, h) + lds_byte(wr * 64 + m * 16 + fr, k * 32 + fq * 8))
; #define LDB(dst, b, h) _Pragma("unroll") for (int n = 0; n < 2; ++n) _Pragma("unroll") for (int k = 0; k < 2; ++k) \
;     dst[n][k] = *reinterpret_cast<const bf16x8*>((char*)SB(b, h) + lds_byte(wc * 32 + n * 16 + fr, k * 32 + fq * 8))
; #define MMA(ai, bj, At, Bq) do { __builtin_amdgcn_s_setprio(1); \
;     _Pragma("unroll") for (int m = 0; m < 4; ++m) _Pragma("unroll") for (int n = 0; n < 2; ++n) _Pragma("unroll") for (int k = 0; k < 2; ++k) \
;       acc[ai][bj][m][n] = __builtin_amdgcn_mfma_f32_16x16x32_bf16(At[m][k], Bq[n][k], acc[ai][bj][m][n], 0, 0, 0); \
;     __builtin_amdgcn_s_setprio(0); } while (0)
; #define WAIT_V(n) asm volatile("s_waitcnt vmcnt(" #n ")" ::: "memory")
; #define WAIT_L(n) asm volatile("s_waitcnt lgkmcnt(" #n ")" ::: "memory")
; #define BAR __builtin_amdgcn_s_barrier()
; #define SCHED __builtin_amdgcn_sched_barrier(0)
; __device__ __forceinline__ void gemm_phase(const int WV, const GemmArgs& g, int tile0) {
;     ...
;       STAGE_B(SB(0, 1), bcol + HALF, t + 2);
;       WAIT_V(6); BAR; MMA(1, 1, At, B1); BAR;
;       LDB(B0, 1, 0); SCHED; LDA(At, 1, 0); STAGE_A(SA(0, 1), brow + HALF, t + 2);
;       WAIT_L(8); BAR; WAIT_L(0); MMA(0, 0, At, B0); BAR; SCHED;
;       LDB(B1, 1, 1); STAGE_B(SB(1, 0), bcol, t + 3);
;       BAR; WAIT_L(0); MMA(0, 1, At, B1); BAR;
;       LDA(At, 1, 1); STAGE_A(SA(1, 0), brow, t + 3);
	s_add_u32 s34, s10, s7
	s_addc_u32 s35, s11, 0
	v_readfirstlane_b32 s7, v142
	v_lshl_add_u64 v[154:155], s[34:35], 1, v[134:135]
	s_mov_b32 m0, s7
	v_readfirstlane_b32 s7, v143
	global_load_lds_dwordx4 v[154:155], off
	v_lshl_add_u64 v[154:155], v[154:155], 0, s[42:43]
	s_mov_b32 m0, s7
	s_nop 0
	global_load_lds_dwordx4 v[154:155], off
	s_waitcnt vmcnt(6)
	s_barrier
	v_mfma_f32_16x16x32_bf16 v[30:33], v[192:195], v[224:227], v[30:33]
	v_mfma_f32_16x16x32_bf16 v[26:29], v[192:195], v[232:235], v[26:29]
	v_mfma_f32_16x16x32_bf16 v[22:25], v[200:203], v[224:227], v[22:25]
	v_mfma_f32_16x16x32_bf16 v[18:21], v[200:203], v[232:235], v[18:21]
	v_mfma_f32_16x16x32_bf16 v[14:17], v[208:211], v[224:227], v[14:17]
	v_mfma_f32_16x16x32_bf16 v[10:13], v[208:211], v[232:235], v[10:13]
	v_mfma_f32_16x16x32_bf16 v[6:9], v[216:219], v[224:227], v[6:9]
	v_mfma_f32_16x16x32_bf16 v[2:5], v[216:219], v[232:235], v[2:5]
	v_mfma_f32_16x16x32_bf16 v[30:33], v[196:199], v[228:231], v[30:33]
	v_mfma_f32_16x16x32_bf16 v[26:29], v[196:199], v[236:239], v[26:29]
	v_mfma_f32_16x16x32_bf16 v[22:25], v[204:207], v[228:231], v[22:25]
	v_mfma_f32_16x16x32_bf16 v[18:21], v[204:207], v[236:239], v[18:21]
	v_mfma_f32_16x16x32_bf16 v[14:17], v[212:215], v[228:231], v[14:17]
	v_mfma_f32_16x16x32_bf16 v[10:13], v[212:215], v[236:239], v[10:13]
	v_mfma_f32_16x16x32_bf16 v[6:9], v[220:223], v[228:231], v[6:9]
	v_mfma_f32_16x16x32_bf16 v[2:5], v[220:223], v[236:239], v[2:5]
	s_barrier
	s_nop 0
	ds_read_b128 v[154:157], v181
	ds_read_b128 v[158:161], v181 offset:1024
	ds_read_b128 v[184:187], v181 offset:2048
	ds_read_b128 v[188:191], v181 offset:3072
	v_readfirstlane_b32 s7, v144
	v_lshl_add_u64 v[224:225], v[240:241], 0, s[38:39]
	s_mov_b32 m0, s7
	v_readfirstlane_b32 s7, v145
	ds_read_b128 v[192:195], v176 offset:32768
	ds_read_b128 v[196:199], v176 offset:33792
	ds_read_b128 v[200:203], v177 offset:32768
	ds_read_b128 v[204:207], v177 offset:33792
	ds_read_b128 v[208:211], v178 offset:32768
	ds_read_b128 v[212:215], v178 offset:33792
	ds_read_b128 v[216:219], v179 offset:32768
	ds_read_b128 v[220:223], v179 offset:33792
	global_load_lds_dwordx4 v[224:225], off
	v_lshl_add_u64 v[224:225], v[242:243], 0, s[38:39]
	s_mov_b32 m0, s7
	s_nop 0
	global_load_lds_dwordx4 v[224:225], off
	s_waitcnt lgkmcnt(8)
	s_barrier
	s_waitcnt lgkmcnt(0)
	s_waitcnt lgkmcnt(0)
	v_mfma_f32_16x16x32_bf16 v[126:129], v[192:195], v[154:157], v[126:129]
	v_mfma_f32_16x16x32_bf16 v[122:125], v[192:195], v[184:187], v[122:125]
	v_mfma_f32_16x16x32_bf16 v[118:121], v[200:203], v[154:157], v[118:121]
	v_mfma_f32_16x16x32_bf16 v[114:117], v[200:203], v[184:187], v[114:117]
	v_mfma_f32_16x16x32_bf16 v[110:113], v[208:211], v[154:157], v[110:113]
	v_mfma_f32_16x16x32_bf16 v[106:109], v[208:211], v[184:187], v[106:109]
	v_mfma_f32_16x16x32_bf16 v[102:105], v[216:219], v[154:157], v[102:105]
	v_mfma_f32_16x16x32_bf16 v[98:101], v[216:219], v[184:187], v[98:101]
	v_mfma_f32_16x16x32_bf16 v[126:129], v[196:199], v[158:161], v[126:129]
	v_mfma_f32_16x16x32_bf16 v[122:125], v[196:199], v[188:191], v[122:125]
	v_mfma_f32_16x16x32_bf16 v[118:121], v[204:207], v[158:161], v[118:121]
	v_mfma_f32_16x16x32_bf16 v[114:117], v[204:207], v[188:191], v[114:117]
	v_mfma_f32_16x16x32_bf16 v[110:113], v[212:215], v[158:161], v[110:113]
	v_mfma_f32_16x16x32_bf16 v[106:109], v[212:215], v[188:191], v[106:109]
	v_mfma_f32_16x16x32_bf16 v[102:105], v[220:223], v[158:161], v[102:105]
	v_mfma_f32_16x16x32_bf16 v[98:101], v[220:223], v[188:191], v[98:101]
	s_barrier
	s_add_i32 s7, s6, 64
	s_cmp_ge_u32 s7, s22
	s_cselect_b32 s34, s23, 0
	s_add_i32 s7, s7, s34
	s_ashr_i32 s25, s7, 31
	s_add_u32 s34, s8, s7
	s_addc_u32 s35, s9, s25
	v_lshl_add_u64 v[240:241], s[34:35], 1, v[134:135]
	v_readfirstlane_b32 s34, v146
	s_mov_b32 m0, s34
	v_readfirstlane_b32 s34, v147
	s_nop 0
	ds_read_b128 v[224:227], v182
	ds_read_b128 v[228:231], v182 offset:1024
	ds_read_b128 v[232:235], v182 offset:2048
	ds_read_b128 v[236:239], v182 offset:3072
	global_load_lds_dwordx4 v[240:241], off
	v_lshl_add_u64 v[240:241], v[240:241], 0, s[42:43]
	s_mov_b32 m0, s34
	s_nop 0
	global_load_lds_dwordx4 v[240:241], off
	s_barrier
	s_waitcnt lgkmcnt(0)
	s_waitcnt lgkmcnt(0)
	v_mfma_f32_16x16x32_bf16 v[94:97], v[192:195], v[224:227], v[94:97]
	v_mfma_f32_16x16x32_bf16 v[90:93], v[192:195], v[232:235], v[90:93]
	v_mfma_f32_16x16x32_bf16 v[86:89], v[200:203], v[224:227], v[86:89]
	v_mfma_f32_16x16x32_bf16 v[82:85], v[200:203], v[232:235], v[82:85]
	v_mfma_f32_16x16x32_bf16 v[78:81], v[208:211], v[224:227], v[78:81]
	v_mfma_f32_16x16x32_bf16 v[74:77], v[208:211], v[232:235], v[74:77]
	v_mfma_f32_16x16x32_bf16 v[70:73], v[216:219], v[224:227], v[70:73]
	v_mfma_f32_16x16x32_bf16 v[66:69], v[216:219], v[232:235], v[66:69]
	v_mfma_f32_16x16x32_bf16 v[94:97], v[196:199], v[228:231], v[94:97]
	v_mfma_f32_16x16x32_bf16 v[90:93], v[196:199], v[236:239], v[90:93]
	v_mfma_f32_16x16x32_bf16 v[86:89], v[204:207], v[228:231], v[86:89]
	v_mfma_f32_16x16x32_bf16 v[82:85], v[204:207], v[236:239], v[82:85]
	v_mfma_f32_16x16x32_bf16 v[78:81], v[212:215], v[228:231], v[78:81]
	v_mfma_f32_16x16x32_bf16 v[74:77], v[212:215], v[236:239], v[74:77]
	v_mfma_f32_16x16x32_bf16 v[70:73], v[220:223], v[228:231], v[70:73]
	v_mfma_f32_16x16x32_bf16 v[66:69], v[220:223], v[236:239], v[66:69]
	v_readfirstlane_b32 s34, v148
	v_lshl_add_u64 v[240:241], v[244:245], 0, s[84:85]
	s_mov_b32 m0, s34
	v_readfirstlane_b32 s34, v149
	s_barrier
; #define STAGE_A(Pp, br, kt) do { const size_t _uo = ((size_t)(br) * g.K + (kt) * BK) * 2; \
;     __builtin_amdgcn_global_load_lds((const unsigned*)(pb + _uo), (unsigned*)((char*)(Pp) + tb0), 16, 0, 0); \
;     __builtin_amdgcn_global_load_lds((const unsigned*)(pb + _uo + (size_t)g.K * 128), (unsigned*)((char*)(Pp) + tb0 + 8192), 16, 0, 0); } while (0)
; #define LDA(dst, b, h) _Pragma("unroll") for (int m = 0; m < 4; ++m) _Pragma("unroll") for (int k = 0; k < 2; ++k) \
;     dst[m][k] = *reinterpret_cast<const bf16x8*>((char*)SA(b, h) + lds_byte(wr * 64 + m * 16 + fr, k * 32 + fq * 8))
; #define LDB(dst, b, h) _Pragma("unroll") for (int n = 0; n < 2; ++n) _Pragma("unroll") for (int k = 0; k < 2; ++k) \
;     dst[n][k] = *reinterpret_cast<const bf16x8*>((char*)SB(b, h) + lds_byte(wc * 32 + n * 16 + fr, k * 32 + fq * 8))
; #define MMA(ai, bj, At, Bq) do { __builtin_amdgcn_s_setprio(1); \
;     _Pragma("unroll") for (int m = 0; m < 4; ++m) _Pragma("unroll") for (int n = 0; n < 2; ++n) _Pragma("unroll") for (int k = 0; k < 2; ++k) \
;       acc[ai][bj][m][n] = __builtin_amdgcn_mfma_f32_16x16x32_bf16(At[m][k], Bq[n][k], acc[ai][bj][m][n], 0, 0, 0); \
;     __builtin_amdgcn_s_setprio(0); } while (0)
; #define WAIT_V(n) asm volatile("s_waitcnt vmcnt(" #n ")" ::: "memory")
; #define WAIT_L(n) asm volatile("s_waitcnt lgkmcnt(" #n ")" ::: "memory")
; #define BAR __builtin_amdgcn_s_barrier()
; #define SCHED __builtin_amdgcn_sched_barrier(0)
; __device__ __forceinline__ void gemm_phase(const int WV, const GemmArgs& g, int tile0) {
;     ...
;       LDA(At, 1, 1); STAGE_A(SA(1, 0), brow, t + 3);
;       BAR; WAIT_L(0); MMA(1, 0, At, B0); BAR; SCHED;
;       STAGE_B(SB(1, 1), bcol + HALF, t + 3);
;       WAIT_V(6); BAR; MMA(1, 1, At, B1); BAR;
;     }
;     { LDB(B0, 0, 0); LDA(At, 0, 0); STAGE_A(SA(1, 1), brow + HALF, nt - 1);
;       BAR; WAIT_L(0); MMA(0, 0, At, B0); BAR;
	s_nop 0
	ds_read_b128 v[192:195], v176 offset:49152
	ds_read_b128 v[196:199], v176 offset:50176
	ds_read_b128 v[200:203], v177 offset:49152
	ds_read_b128 v[204:207], v177 offset:50176
	ds_read_b128 v[208:211], v178 offset:49152
	ds_read_b128 v[212:215], v178 offset:50176
	ds_read_b128 v[216:219], v179 offset:49152
	ds_read_b128 v[220:223], v179 offset:50176
	global_load_lds_dwordx4 v[240:241], off
	v_lshl_add_u64 v[240:241], v[246:247], 0, s[84:85]
	s_mov_b32 m0, s34
	s_nop 0
	global_load_lds_dwordx4 v[240:241], off
	s_barrier
	s_waitcnt lgkmcnt(0)
	s_waitcnt lgkmcnt(0)
	v_mfma_f32_16x16x32_bf16 v[62:65], v[192:195], v[154:157], v[62:65]
	v_mfma_f32_16x16x32_bf16 v[58:61], v[192:195], v[184:187], v[58:61]
	v_mfma_f32_16x16x32_bf16 v[54:57], v[200:203], v[154:157], v[54:57]
	v_mfma_f32_16x16x32_bf16 v[50:53], v[200:203], v[184:187], v[50:53]
	v_mfma_f32_16x16x32_bf16 v[46:49], v[208:211], v[154:157], v[46:49]
	v_mfma_f32_16x16x32_bf16 v[42:45], v[208:211], v[184:187], v[42:45]
	v_mfma_f32_16x16x32_bf16 v[38:41], v[216:219], v[154:157], v[38:41]
	v_mfma_f32_16x16x32_bf16 v[34:37], v[216:219], v[184:187], v[34:37]
	v_mfma_f32_16x16x32_bf16 v[62:65], v[196:199], v[158:161], v[62:65]
	v_mfma_f32_16x16x32_bf16 v[58:61], v[196:199], v[188:191], v[58:61]
	v_mfma_f32_16x16x32_bf16 v[54:57], v[204:207], v[158:161], v[54:57]
	v_mfma_f32_16x16x32_bf16 v[50:53], v[204:207], v[188:191], v[50:53]
	v_mfma_f32_16x16x32_bf16 v[46:49], v[212:215], v[158:161], v[46:49]
	v_mfma_f32_16x16x32_bf16 v[42:45], v[212:215], v[188:191], v[42:45]
	v_mfma_f32_16x16x32_bf16 v[38:41], v[220:223], v[158:161], v[38:41]
	v_mfma_f32_16x16x32_bf16 v[34:37], v[220:223], v[188:191], v[34:37]
	s_barrier
	s_add_u32 s34, s10, s7
	s_addc_u32 s35, s11, s25
	v_readfirstlane_b32 s7, v150
	v_lshl_add_u64 v[154:155], s[34:35], 1, v[134:135]
	s_mov_b32 m0, s7
	v_readfirstlane_b32 s7, v151
	global_load_lds_dwordx4 v[154:155], off
	v_lshl_add_u64 v[154:155], v[154:155], 0, s[42:43]
	s_mov_b32 m0, s7
	s_nop 0
	global_load_lds_dwordx4 v[154:155], off
	s_waitcnt vmcnt(6)
	s_barrier
	v_mfma_f32_16x16x32_bf16 v[30:33], v[192:195], v[224:227], v[30:33]
	v_mfma_f32_16x16x32_bf16 v[26:29], v[192:195], v[232:235], v[26:29]
	v_mfma_f32_16x16x32_bf16 v[22:25], v[200:203], v[224:227], v[22:25]
	v_mfma_f32_16x16x32_bf16 v[18:21], v[200:203], v[232:235], v[18:21]
	v_mfma_f32_16x16x32_bf16 v[14:17], v[208:211], v[224:227], v[14:17]
	v_mfma_f32_16x16x32_bf16 v[10:13], v[208:211], v[232:235], v[10:13]
	v_mfma_f32_16x16x32_bf16 v[6:9], v[216:219], v[224:227], v[6:9]
	v_mfma_f32_16x16x32_bf16 v[2:5], v[216:219], v[232:235], v[2:5]
	v_mfma_f32_16x16x32_bf16 v[30:33], v[196:199], v[228:231], v[30:33]
	v_mfma_f32_16x16x32_bf16 v[26:29], v[196:199], v[236:239], v[26:29]
	v_mfma_f32_16x16x32_bf16 v[22:25], v[204:207], v[228:231], v[22:25]
	v_mfma_f32_16x16x32_bf16 v[18:21], v[204:207], v[236:239], v[18:21]
	v_mfma_f32_16x16x32_bf16 v[14:17], v[212:215], v[228:231], v[14:17]
	v_mfma_f32_16x16x32_bf16 v[10:13], v[212:215], v[236:239], v[10:13]
	v_mfma_f32_16x16x32_bf16 v[6:9], v[220:223], v[228:231], v[6:9]
	v_mfma_f32_16x16x32_bf16 v[2:5], v[220:223], v[236:239], v[2:5]
	s_add_u32 s12, s12, 0x100
	s_addc_u32 s13, s13, 0
	s_add_u32 s20, s20, 0x100
	s_addc_u32 s21, s21, 0
	s_add_u32 vcc_lo, vcc_lo, 0x100
	s_addc_u32 vcc_hi, vcc_hi, 0
	s_add_u32 s26, s26, 0x100
	s_addc_u32 s27, s27, 0
	s_addk_i32 s6, 0x80
	s_cmp_ge_i32 s56, s47
	s_barrier
	s_cbranch_scc0 .LBB0_433
	s_mul_i32 s6, s4, s24
	v_readlane_b32 s8, v250, 54
	s_mul_hi_i32 s7, s4, s24
	s_add_u32 s6, s6, s8
	s_addc_u32 s7, s7, 0
	v_lshl_add_u64 v[212:213], s[6:7], 1, v[136:137]
	v_readfirstlane_b32 s6, v152
	s_mov_b32 m0, s6
	v_readfirstlane_b32 s6, v153
	s_nop 0
	ds_read_b128 v[140:143], v175
	ds_read_b128 v[144:147], v175 offset:1024
	ds_read_b128 v[148:151], v175 offset:2048
	ds_read_b128 v[154:157], v175 offset:3072
	ds_read_b128 v[158:161], v176
	ds_read_b128 v[184:187], v176 offset:1024
	ds_read_b128 v[188:191], v177
	ds_read_b128 v[192:195], v177 offset:1024
	ds_read_b128 v[196:199], v178
	ds_read_b128 v[200:203], v178 offset:1024
	ds_read_b128 v[204:207], v179
	ds_read_b128 v[208:211], v179 offset:1024
	global_load_lds_dwordx4 v[212:213], off
	v_lshl_add_u64 v[212:213], v[212:213], 0, s[28:29]
	s_mov_b32 m0, s6
	s_nop 0
	global_load_lds_dwordx4 v[212:213], off
	s_barrier
	s_waitcnt lgkmcnt(0)
	s_waitcnt lgkmcnt(0)
	v_mfma_f32_16x16x32_bf16 v[126:129], v[158:161], v[140:143], v[126:129]
	v_mfma_f32_16x16x32_bf16 v[122:125], v[158:161], v[148:151], v[122:125]
	v_mfma_f32_16x16x32_bf16 v[118:121], v[188:191], v[140:143], v[118:121]
	v_mfma_f32_16x16x32_bf16 v[114:117], v[188:191], v[148:151], v[114:117]
	v_mfma_f32_16x16x32_bf16 v[102:105], v[204:207], v[140:143], v[102:105]
	v_mfma_f32_16x16x32_bf16 v[98:101], v[204:207], v[148:151], v[98:101]
	v_mfma_f32_16x16x32_bf16 v[126:129], v[184:187], v[144:147], v[126:129]
	v_mfma_f32_16x16x32_bf16 v[122:125], v[184:187], v[154:157], v[122:125]
	v_mfma_f32_16x16x32_bf16 v[118:121], v[192:195], v[144:147], v[118:121]
	v_mfma_f32_16x16x32_bf16 v[114:117], v[192:195], v[154:157], v[114:117]
	v_mfma_f32_16x16x32_bf16 v[110:113], v[196:199], v[140:143], v[110:113]
	v_mfma_f32_16x16x32_bf16 v[106:109], v[196:199], v[148:151], v[106:109]
	v_mfma_f32_16x16x32_bf16 v[102:105], v[208:211], v[144:147], v[102:105]
	v_mfma_f32_16x16x32_bf16 v[98:101], v[208:211], v[154:157], v[98:101]
	v_mfma_f32_16x16x32_bf16 v[212:215], v[200:203], v[144:147], v[110:113]
	v_mfma_f32_16x16x32_bf16 v[216:219], v[200:203], v[154:157], v[106:109]
	s_barrier
; #define LDA(dst, b, h) _Pragma("unroll") for (int m = 0; m < 4; ++m) _Pragma("unroll") for (int k = 0; k < 2; ++k) \
;     dst[m][k] = *reinterpret_cast<const bf16x8*>((char*)SA(b, h) + lds_byte(wr * 64 + m * 16 + fr, k * 32 + fq * 8))
; #define LDB(dst, b, h) _Pragma("unroll") for (int n = 0; n < 2; ++n) _Pragma("unroll") for (int k = 0; k < 2; ++k) \
;     dst[n][k] = *reinterpret_cast<const bf16x8*>((char*)SB(b, h) + lds_byte(wc * 32 + n * 16 + fr, k * 32 + fq * 8))
; #define MMA(ai, bj, At, Bq) do { __builtin_amdgcn_s_setprio(1); \
;     _Pragma("unroll") for (int m = 0; m < 4; ++m) _Pragma("unroll") for (int n = 0; n < 2; ++n) _Pragma("unroll") for (int k = 0; k < 2; ++k) \
;       acc[ai][bj][m][n] = __builtin_amdgcn_mfma_f32_16x16x32_bf16(At[m][k], Bq[n][k], acc[ai][bj][m][n], 0, 0, 0); \
;     __builtin_amdgcn_s_setprio(0); } while (0)
; #define WAIT_V(n) asm volatile("s_waitcnt vmcnt(" #n ")" ::: "memory")
; #define WAIT_L(n) asm volatile("s_waitcnt lgkmcnt(" #n ")" ::: "memory")
; #define BAR __builtin_amdgcn_s_barrier()
; __device__ __forceinline__ void gemm_phase(const int WV, const GemmArgs& g, int tile0) {
;     ...
;       LDB(B1, 0, 1); BAR; WAIT_L(0); MMA(0, 1, At, B1); BAR;
;       LDA(At, 0, 1); WAIT_V(4); BAR; WAIT_L(0); MMA(1, 0, At, B0); MMA(1, 1, At, B1); BAR; }
;     { LDB(B0, 1, 0); LDA(At, 1, 0); WAIT_V(2); BAR; WAIT_L(0); MMA(0, 0, At, B0); BAR;
	s_nop 0
	s_nop 0
	ds_read_b128 v[106:109], v180
	ds_read_b128 v[110:113], v180 offset:1024
	ds_read_b128 v[220:223], v180 offset:2048
	ds_read_b128 v[224:227], v180 offset:3072
	s_barrier
	s_waitcnt lgkmcnt(0)
	s_waitcnt lgkmcnt(3)
	v_mfma_f32_16x16x32_bf16 v[86:89], v[188:191], v[106:109], v[86:89]
	s_waitcnt lgkmcnt(1)
	v_mfma_f32_16x16x32_bf16 v[82:85], v[188:191], v[220:223], v[82:85]
	v_mfma_f32_16x16x32_bf16 v[70:73], v[204:207], v[106:109], v[70:73]
	v_mfma_f32_16x16x32_bf16 v[66:69], v[204:207], v[220:223], v[66:69]
	v_mfma_f32_16x16x32_bf16 v[94:97], v[158:161], v[106:109], v[94:97]
	v_mfma_f32_16x16x32_bf16 v[90:93], v[158:161], v[220:223], v[90:93]
	v_mfma_f32_16x16x32_bf16 v[86:89], v[192:195], v[110:113], v[86:89]
	s_waitcnt lgkmcnt(0)
	v_mfma_f32_16x16x32_bf16 v[82:85], v[192:195], v[224:227], v[82:85]
	v_mfma_f32_16x16x32_bf16 v[78:81], v[196:199], v[106:109], v[78:81]
	v_mfma_f32_16x16x32_bf16 v[74:77], v[196:199], v[220:223], v[74:77]
	v_mfma_f32_16x16x32_bf16 v[70:73], v[208:211], v[110:113], v[70:73]
	v_mfma_f32_16x16x32_bf16 v[66:69], v[208:211], v[224:227], v[66:69]
	v_mfma_f32_16x16x32_bf16 v[228:231], v[184:187], v[110:113], v[94:97]
	v_mfma_f32_16x16x32_bf16 v[158:161], v[184:187], v[224:227], v[90:93]
	v_mfma_f32_16x16x32_bf16 v[184:187], v[200:203], v[110:113], v[78:81]
	v_mfma_f32_16x16x32_bf16 v[188:191], v[200:203], v[224:227], v[74:77]
	s_barrier
	s_nop 0
	ds_read_b128 v[74:77], v176 offset:16384
	ds_read_b128 v[78:81], v176 offset:17408
	ds_read_b128 v[90:93], v177 offset:16384
	ds_read_b128 v[94:97], v177 offset:17408
	ds_read_b128 v[192:195], v178 offset:16384
	ds_read_b128 v[196:199], v178 offset:17408
	ds_read_b128 v[200:203], v179 offset:16384
	ds_read_b128 v[204:207], v179 offset:17408
	s_waitcnt vmcnt(4)
	s_barrier
	s_waitcnt lgkmcnt(0)
	s_waitcnt lgkmcnt(7)
	v_mfma_f32_16x16x32_bf16 v[62:65], v[74:77], v[140:143], v[62:65]
	v_mfma_f32_16x16x32_bf16 v[58:61], v[74:77], v[148:151], v[58:61]
	s_waitcnt lgkmcnt(5)
	v_mfma_f32_16x16x32_bf16 v[54:57], v[90:93], v[140:143], v[54:57]
	v_mfma_f32_16x16x32_bf16 v[50:53], v[90:93], v[148:151], v[50:53]
	s_waitcnt lgkmcnt(1)
	v_mfma_f32_16x16x32_bf16 v[38:41], v[200:203], v[140:143], v[38:41]
	v_mfma_f32_16x16x32_bf16 v[34:37], v[200:203], v[148:151], v[34:37]
	v_mfma_f32_16x16x32_bf16 v[62:65], v[78:81], v[144:147], v[62:65]
	v_mfma_f32_16x16x32_bf16 v[58:61], v[78:81], v[154:157], v[58:61]
	v_mfma_f32_16x16x32_bf16 v[54:57], v[94:97], v[144:147], v[54:57]
	v_mfma_f32_16x16x32_bf16 v[50:53], v[94:97], v[154:157], v[50:53]
	v_mfma_f32_16x16x32_bf16 v[46:49], v[192:195], v[140:143], v[46:49]
	v_mfma_f32_16x16x32_bf16 v[42:45], v[192:195], v[148:151], v[42:45]
	s_waitcnt lgkmcnt(0)
	v_mfma_f32_16x16x32_bf16 v[38:41], v[204:207], v[144:147], v[38:41]
	v_mfma_f32_16x16x32_bf16 v[34:37], v[204:207], v[154:157], v[34:37]
	v_mfma_f32_16x16x32_bf16 v[208:211], v[196:199], v[144:147], v[46:49]
	v_mfma_f32_16x16x32_bf16 v[232:235], v[196:199], v[154:157], v[42:45]
	v_mfma_f32_16x16x32_bf16 v[22:25], v[90:93], v[106:109], v[22:25]
	v_mfma_f32_16x16x32_bf16 v[18:21], v[90:93], v[220:223], v[18:21]
	v_mfma_f32_16x16x32_bf16 v[6:9], v[200:203], v[106:109], v[6:9]
	v_mfma_f32_16x16x32_bf16 v[2:5], v[200:203], v[220:223], v[2:5]
	v_mfma_f32_16x16x32_bf16 v[30:33], v[74:77], v[106:109], v[30:33]
	v_mfma_f32_16x16x32_bf16 v[26:29], v[74:77], v[220:223], v[26:29]
	v_mfma_f32_16x16x32_bf16 v[22:25], v[94:97], v[110:113], v[22:25]
	v_mfma_f32_16x16x32_bf16 v[18:21], v[94:97], v[224:227], v[18:21]
	v_mfma_f32_16x16x32_bf16 v[14:17], v[192:195], v[106:109], v[14:17]
	v_mfma_f32_16x16x32_bf16 v[10:13], v[192:195], v[220:223], v[10:13]
	v_mfma_f32_16x16x32_bf16 v[6:9], v[204:207], v[110:113], v[6:9]
	v_mfma_f32_16x16x32_bf16 v[2:5], v[204:207], v[224:227], v[2:5]
	v_mfma_f32_16x16x32_bf16 v[140:143], v[78:81], v[110:113], v[30:33]
	v_mfma_f32_16x16x32_bf16 v[144:147], v[78:81], v[224:227], v[26:29]
	v_mfma_f32_16x16x32_bf16 v[148:151], v[196:199], v[110:113], v[14:17]
	v_mfma_f32_16x16x32_bf16 v[152:155], v[196:199], v[224:227], v[10:13]
	s_barrier
	s_nop 0
	ds_read_b128 v[10:13], v181
	ds_read_b128 v[14:17], v181 offset:1024
	ds_read_b128 v[192:195], v181 offset:2048
	ds_read_b128 v[196:199], v181 offset:3072
	ds_read_b128 v[26:29], v176 offset:32768
	ds_read_b128 v[30:33], v176 offset:33792
	ds_read_b128 v[42:45], v177 offset:32768
	ds_read_b128 v[46:49], v177 offset:33792
	ds_read_b128 v[200:203], v178 offset:32768
	ds_read_b128 v[204:207], v178 offset:33792
	ds_read_b128 v[220:223], v179 offset:32768
	ds_read_b128 v[224:227], v179 offset:33792
	s_waitcnt vmcnt(2)
	s_barrier
; #define opaque_tid() opaque_tid_(WV)
; #define LDA(dst, b, h) _Pragma("unroll") for (int m = 0; m < 4; ++m) _Pragma("unroll") for (int k = 0; k < 2; ++k) \
;     dst[m][k] = *reinterpret_cast<const bf16x8*>((char*)SA(b, h) + lds_byte(wr * 64 + m * 16 + fr, k * 32 + fq * 8))
; #define LDB(dst, b, h) _Pragma("unroll") for (int n = 0; n < 2; ++n) _Pragma("unroll") for (int k = 0; k < 2; ++k) \
;     dst[n][k] = *reinterpret_cast<const bf16x8*>((char*)SB(b, h) + lds_byte(wc * 32 + n * 16 + fr, k * 32 + fq * 8))
; #define MMA(ai, bj, At, Bq) do { __builtin_amdgcn_s_setprio(1); \
;     _Pragma("unroll") for (int m = 0; m < 4; ++m) _Pragma("unroll") for (int n = 0; n < 2; ++n) _Pragma("unroll") for (int k = 0; k < 2; ++k) \
;       acc[ai][bj][m][n] = __builtin_amdgcn_mfma_f32_16x16x32_bf16(At[m][k], Bq[n][k], acc[ai][bj][m][n], 0, 0, 0); \
;     __builtin_amdgcn_s_setprio(0); } while (0)
; #define WAIT_V(n) asm volatile("s_waitcnt vmcnt(" #n ")" ::: "memory")
; #define WAIT_L(n) asm volatile("s_waitcnt lgkmcnt(" #n ")" ::: "memory")
; #define BAR __builtin_amdgcn_s_barrier()
; __device__ __forceinline__ void gemm_phase(const int WV, const GemmArgs& g, int tile0) {
;     ...
;     { LDB(B0, 1, 0); LDA(At, 1, 0); WAIT_V(2); BAR; WAIT_L(0); MMA(0, 0, At, B0); BAR;
;       LDB(B1, 1, 1); WAIT_V(0); BAR; WAIT_L(0); MMA(0, 1, At, B1); BAR;
;       LDA(At, 1, 1); BAR; WAIT_L(0); MMA(1, 0, At, B0); MMA(1, 1, At, B1); BAR; }
;     if (wr == 0) BAR;
;     const int tid2 = opaque_tid();
;     const int e_wr = tid2 >> 8, e_wc = (tid2 >> 6) & 3, e_fr = tid2 & 15, e_fq = (tid2 >> 4) & 3;
;     const int tok0 = bcol + e_wc * 32 + e_fr;
;     float rs[4] = {1.f, 1.f, 1.f, 1.f}, sq[4] = {0.f, 0.f, 0.f, 0.f};
;     if (EPI == EPI_IN || EPI == EPI_FF1 || EPI == EPI_PLE) {
	s_waitcnt lgkmcnt(0)
	s_waitcnt lgkmcnt(7)
	v_mfma_f32_16x16x32_bf16 v[74:77], v[26:29], v[10:13], v[126:129]
	s_waitcnt lgkmcnt(6)
	v_mfma_f32_16x16x32_bf16 v[126:129], v[30:33], v[14:17], v[74:77]
	v_mfma_f32_16x16x32_bf16 v[74:77], v[26:29], v[192:195], v[122:125]
	v_mfma_f32_16x16x32_bf16 v[122:125], v[30:33], v[196:199], v[74:77]
	s_waitcnt lgkmcnt(5)
	v_mfma_f32_16x16x32_bf16 v[74:77], v[42:45], v[10:13], v[118:121]
	s_waitcnt lgkmcnt(4)
	v_mfma_f32_16x16x32_bf16 v[110:113], v[46:49], v[14:17], v[74:77]
	v_mfma_f32_16x16x32_bf16 v[74:77], v[42:45], v[192:195], v[114:117]
	v_mfma_f32_16x16x32_bf16 v[106:109], v[46:49], v[196:199], v[74:77]
	s_waitcnt lgkmcnt(3)
	v_mfma_f32_16x16x32_bf16 v[74:77], v[200:203], v[10:13], v[212:215]
	s_waitcnt lgkmcnt(2)
	v_mfma_f32_16x16x32_bf16 v[94:97], v[204:207], v[14:17], v[74:77]
	v_mfma_f32_16x16x32_bf16 v[74:77], v[200:203], v[192:195], v[216:219]
	v_mfma_f32_16x16x32_bf16 v[90:93], v[204:207], v[196:199], v[74:77]
	s_waitcnt lgkmcnt(1)
	v_mfma_f32_16x16x32_bf16 v[74:77], v[220:223], v[10:13], v[102:105]
	s_waitcnt lgkmcnt(0)
	v_mfma_f32_16x16x32_bf16 v[78:81], v[224:227], v[14:17], v[74:77]
	v_mfma_f32_16x16x32_bf16 v[74:77], v[220:223], v[192:195], v[98:101]
	v_mfma_f32_16x16x32_bf16 v[74:77], v[224:227], v[196:199], v[74:77]
	s_barrier
	ds_read_b128 v[212:215], v182
	ds_read_b128 v[216:219], v182 offset:1024
	ds_read_b128 v[236:239], v182 offset:2048
	ds_read_b128 v[240:243], v182 offset:3072
	s_waitcnt vmcnt(0)
	s_barrier
	s_waitcnt lgkmcnt(0)
	s_waitcnt lgkmcnt(3)
	v_mfma_f32_16x16x32_bf16 v[98:101], v[26:29], v[212:215], v[228:231]
	s_waitcnt lgkmcnt(1)
	v_mfma_f32_16x16x32_bf16 v[26:29], v[26:29], v[236:239], v[158:161]
	s_waitcnt lgkmcnt(0)
	v_mfma_f32_16x16x32_bf16 v[114:117], v[30:33], v[240:243], v[26:29]
	v_mfma_f32_16x16x32_bf16 v[26:29], v[42:45], v[212:215], v[86:89]
	v_mfma_f32_16x16x32_bf16 v[102:105], v[46:49], v[216:219], v[26:29]
	v_mfma_f32_16x16x32_bf16 v[26:29], v[42:45], v[236:239], v[82:85]
	v_mfma_f32_16x16x32_bf16 v[118:121], v[30:33], v[216:219], v[98:101]
	v_mfma_f32_16x16x32_bf16 v[98:101], v[46:49], v[240:243], v[26:29]
	v_mfma_f32_16x16x32_bf16 v[26:29], v[200:203], v[212:215], v[184:187]
	v_mfma_f32_16x16x32_bf16 v[86:89], v[204:207], v[216:219], v[26:29]
	v_mfma_f32_16x16x32_bf16 v[26:29], v[200:203], v[236:239], v[188:191]
	v_mfma_f32_16x16x32_bf16 v[82:85], v[204:207], v[240:243], v[26:29]
	v_mfma_f32_16x16x32_bf16 v[26:29], v[220:223], v[212:215], v[70:73]
	v_mfma_f32_16x16x32_bf16 v[70:73], v[224:227], v[216:219], v[26:29]
	v_mfma_f32_16x16x32_bf16 v[26:29], v[220:223], v[236:239], v[66:69]
	v_mfma_f32_16x16x32_bf16 v[66:69], v[224:227], v[240:243], v[26:29]
	s_barrier
	ds_read_b128 v[156:159], v176 offset:49152
	ds_read_b128 v[184:187], v176 offset:50176
	ds_read_b128 v[188:191], v177 offset:49152
	ds_read_b128 v[200:203], v177 offset:50176
	ds_read_b128 v[204:207], v178 offset:49152
	ds_read_b128 v[220:223], v178 offset:50176
	ds_read_b128 v[224:227], v179 offset:49152
	ds_read_b128 v[228:231], v179 offset:50176
	s_barrier
	s_waitcnt lgkmcnt(0)
	s_waitcnt lgkmcnt(7)
	v_mfma_f32_16x16x32_bf16 v[26:29], v[156:159], v[10:13], v[62:65]
	s_waitcnt lgkmcnt(6)
	v_mfma_f32_16x16x32_bf16 v[62:65], v[184:187], v[14:17], v[26:29]
	v_mfma_f32_16x16x32_bf16 v[26:29], v[156:159], v[192:195], v[58:61]
	v_mfma_f32_16x16x32_bf16 v[58:61], v[184:187], v[196:199], v[26:29]
	s_waitcnt lgkmcnt(5)
	v_mfma_f32_16x16x32_bf16 v[26:29], v[188:191], v[10:13], v[54:57]
	s_waitcnt lgkmcnt(4)
	v_mfma_f32_16x16x32_bf16 v[46:49], v[200:203], v[14:17], v[26:29]
	v_mfma_f32_16x16x32_bf16 v[26:29], v[188:191], v[192:195], v[50:53]
	v_mfma_f32_16x16x32_bf16 v[42:45], v[200:203], v[196:199], v[26:29]
	s_waitcnt lgkmcnt(3)
	v_mfma_f32_16x16x32_bf16 v[26:29], v[204:207], v[10:13], v[208:211]
	s_waitcnt lgkmcnt(1)
	v_mfma_f32_16x16x32_bf16 v[10:13], v[224:227], v[10:13], v[38:41]
	v_mfma_f32_16x16x32_bf16 v[30:33], v[220:223], v[14:17], v[26:29]
	v_mfma_f32_16x16x32_bf16 v[26:29], v[204:207], v[192:195], v[232:235]
	s_waitcnt lgkmcnt(0)
	v_mfma_f32_16x16x32_bf16 v[14:17], v[228:231], v[14:17], v[10:13]
	v_mfma_f32_16x16x32_bf16 v[10:13], v[224:227], v[192:195], v[34:37]
	v_mfma_f32_16x16x32_bf16 v[26:29], v[220:223], v[196:199], v[26:29]
	v_mfma_f32_16x16x32_bf16 v[10:13], v[228:231], v[196:199], v[10:13]
	v_mfma_f32_16x16x32_bf16 v[34:37], v[156:159], v[212:215], v[140:143]
	v_mfma_f32_16x16x32_bf16 v[54:57], v[184:187], v[216:219], v[34:37]
	v_mfma_f32_16x16x32_bf16 v[34:37], v[156:159], v[236:239], v[144:147]
	v_mfma_f32_16x16x32_bf16 v[18:21], v[188:191], v[236:239], v[18:21]
	v_mfma_f32_16x16x32_bf16 v[50:53], v[184:187], v[240:243], v[34:37]
	v_mfma_f32_16x16x32_bf16 v[22:25], v[188:191], v[212:215], v[22:25]
	v_mfma_f32_16x16x32_bf16 v[34:37], v[200:203], v[240:243], v[18:21]
	v_mfma_f32_16x16x32_bf16 v[18:21], v[204:207], v[212:215], v[148:151]
	v_mfma_f32_16x16x32_bf16 v[38:41], v[200:203], v[216:219], v[22:25]
	v_mfma_f32_16x16x32_bf16 v[22:25], v[220:223], v[216:219], v[18:21]
	v_mfma_f32_16x16x32_bf16 v[18:21], v[204:207], v[236:239], v[152:155]
	v_mfma_f32_16x16x32_bf16 v[6:9], v[224:227], v[212:215], v[6:9]
	v_mfma_f32_16x16x32_bf16 v[2:5], v[224:227], v[236:239], v[2:5]
	v_mfma_f32_16x16x32_bf16 v[18:21], v[220:223], v[240:243], v[18:21]
	v_mfma_f32_16x16x32_bf16 v[6:9], v[228:231], v[216:219], v[6:9]
	v_mfma_f32_16x16x32_bf16 v[2:5], v[228:231], v[240:243], v[2:5]
	s_barrier
	s_mov_b64 s[8:9], exec
	v_readlane_b32 s6, v250, 55
	v_readlane_b32 s7, v250, 56
	s_and_b64 s[6:7], s[8:9], s[6:7]
	s_mov_b64 exec, s[6:7]
	s_cbranch_execz .LBB0_436
	s_barrier
.LBB0_436:
	s_setprio 0
	s_or_b64 exec, exec, s[8:9]
	v_mov_b32_e32 v0, v162
	s_cmp_lt_i32 s55, 2
	s_cbranch_scc1 .LBB0_439
	s_cmp_gt_i32 s55, 3
	s_cbranch_scc0 .LBB0_440
	s_cmp_eq_u32 s55, 4
	s_cselect_b64 s[8:9], -1, 0
	s_cbranch_execz .LBB0_441
	s_branch .LBB0_442
